# attention item: the four SGB gate loads of the item tail are issued at item start (after the chunk loads) into spare registers; the tail copies them
# speedup vs baseline: 1.0031x; 1.0019x over previous
.LBB0_456:
	s_or_b64 exec, exec, s[82:83]
	v_readlane_b32 s0, v245, 48
	v_lshlrev_b32_e32 v34, 6, v184
	v_readlane_b32 s1, v245, 49
	v_lshlrev_b32_e32 v46, 1, v34
	v_mov_b32_e32 v47, v133
	v_lshl_add_u64 v[36:37], s[0:1], 0, v[150:151]
	v_lshl_add_u64 v[34:35], v[36:37], 0, v[46:47]
	v_mov_b32_e32 v145, v133
	v_lshl_add_u64 v[48:49], v[34:35], 0, v[144:145]
	s_waitcnt vmcnt(4)
	v_mov_b32_e32 v34, v226
	v_mov_b32_e32 v35, v227
	v_mov_b32_e32 v36, v228
	v_mov_b32_e32 v37, v229
	v_mov_b32_e32 v38, v230
	v_mov_b32_e32 v39, v231
	v_mov_b32_e32 v40, v232
	v_mov_b32_e32 v41, v233
	v_mov_b32_e32 v42, v234
	v_mov_b32_e32 v43, v235
	v_mov_b32_e32 v44, v236
	v_mov_b32_e32 v45, v237
	v_lshlrev_b64 v[50:51], 11, v[146:147]
	v_lshl_add_u64 v[50:51], s[96:97], 0, v[50:51]
	v_lshl_add_u64 v[50:51], v[50:51], 0, v[46:47]
	v_mov_b32_e32 v46, v238
	v_mov_b32_e32 v47, v239
	v_mov_b32_e32 v48, v240
	v_mov_b32_e32 v49, v241
	ds_bpermute_b32 v54, v172, v149
	v_permlane32_swap_b32_e32 v2, v18
	v_permlane32_swap_b32_e32 v3, v19
	s_waitcnt lgkmcnt(0)
	v_add_f32_e32 v54, v149, v54
	v_rcp_f32_e32 v54, v54
	v_permlane32_swap_b32_e32 v4, v20
	v_permlane32_swap_b32_e32 v5, v21
	v_permlane32_swap_b32_e32 v6, v22
	v_permlane32_swap_b32_e32 v7, v23
	v_permlane32_swap_b32_e32 v8, v24
	v_permlane32_swap_b32_e32 v9, v25
	s_mov_b64 s[0:1], 0x13a0400
	s_mov_b32 s3, 0x13a0000
	v_lshl_add_u64 v[50:51], v[50:51], 0, v[144:145]
	v_pk_mul_f32 v[2:3], v[54:55], v[2:3] op_sel_hi:[0,1]
	v_pk_mul_f32 v[18:19], v[54:55], v[18:19] op_sel_hi:[0,1]
	v_pk_mul_f32 v[4:5], v[54:55], v[4:5] op_sel_hi:[0,1]
	v_pk_mul_f32 v[20:21], v[54:55], v[20:21] op_sel_hi:[0,1]
	v_pk_mul_f32 v[22:23], v[54:55], v[22:23] op_sel_hi:[0,1]
	v_pk_mul_f32 v[24:25], v[54:55], v[24:25] op_sel_hi:[0,1]
	v_lshl_add_u64 v[52:53], v[50:51], 0, s[0:1]
	v_add_co_u32_e32 v50, vcc, s3, v50
	v_pk_mul_f32 v[6:7], v[54:55], v[6:7] op_sel_hi:[0,1]
	v_pk_mul_f32 v[8:9], v[54:55], v[8:9] op_sel_hi:[0,1]
	v_permlane32_swap_b32_e32 v10, v26
	v_addc_co_u32_e32 v51, vcc, 0, v51, vcc
	v_permlane32_swap_b32_e32 v11, v27
	v_permlane32_swap_b32_e32 v12, v28
	v_permlane32_swap_b32_e32 v13, v29
	v_permlane32_swap_b32_e32 v14, v30
	v_permlane32_swap_b32_e32 v15, v31
	v_permlane32_swap_b32_e32 v16, v32
	v_permlane32_swap_b32_e32 v17, v33
	v_add_u32_e32 v161, s78, v161
	s_movk_i32 s0, 0x5ff
	v_cmp_lt_i32_e32 vcc, s0, v161
	s_or_b64 s[84:85], vcc, s[84:85]
	v_lshlrev_b32_e32 v56, 16, v34
	v_and_b32_e32 v57, 0xffff0000, v34
	v_lshlrev_b32_e32 v34, 16, v35
	v_and_b32_e32 v35, 0xffff0000, v35
	v_lshlrev_b32_e32 v58, 16, v36
	v_and_b32_e32 v59, 0xffff0000, v36
	v_lshlrev_b32_e32 v36, 16, v37
	v_and_b32_e32 v37, 0xffff0000, v37
	v_lshlrev_b32_e32 v62, 16, v40
	v_and_b32_e32 v63, 0xffff0000, v40
	v_lshlrev_b32_e32 v40, 16, v41
	v_and_b32_e32 v41, 0xffff0000, v41
	v_lshlrev_b32_e32 v60, 16, v38
	v_and_b32_e32 v61, 0xffff0000, v38
	v_lshlrev_b32_e32 v38, 16, v39
	v_and_b32_e32 v39, 0xffff0000, v39
	v_pk_mul_f32 v[2:3], v[2:3], v[56:57]
	v_pk_mul_f32 v[18:19], v[18:19], v[58:59]
	v_pk_mul_f32 v[34:35], v[4:5], v[34:35]
	v_pk_mul_f32 v[20:21], v[20:21], v[36:37]
	v_pk_mul_f32 v[22:23], v[22:23], v[62:63]
	v_pk_mul_f32 v[24:25], v[24:25], v[40:41]
	v_pk_mul_f32 v[6:7], v[6:7], v[60:61]
	v_pk_mul_f32 v[36:37], v[8:9], v[38:39]
	v_cvt_pk_bf16_f32 v2, v2, v3
	v_cvt_pk_bf16_f32 v4, v18, v19
	v_cvt_pk_bf16_f32 v3, v34, v35
	v_cvt_pk_bf16_f32 v5, v20, v21
	v_cvt_pk_bf16_f32 v8, v22, v23
	v_cvt_pk_bf16_f32 v9, v24, v25
	v_lshlrev_b32_e32 v64, 16, v42
	v_and_b32_e32 v65, 0xffff0000, v42
	v_lshlrev_b32_e32 v42, 16, v43
	v_and_b32_e32 v43, 0xffff0000, v43
	v_cvt_pk_bf16_f32 v6, v6, v7
	v_cvt_pk_bf16_f32 v7, v36, v37
	global_store_dwordx4 v[50:51], v[2:5], off offset:1024
	global_store_dwordx4 v[52:53], v[6:9], off offset:16
	v_lshlrev_b32_e32 v66, 16, v44
	v_pk_mul_f32 v[2:3], v[54:55], v[10:11] op_sel_hi:[0,1]
	v_pk_mul_f32 v[8:9], v[54:55], v[12:13] op_sel_hi:[0,1]
	v_pk_mul_f32 v[2:3], v[2:3], v[64:65]
	v_pk_mul_f32 v[8:9], v[8:9], v[42:43]
	v_and_b32_e32 v67, 0xffff0000, v44
	v_cvt_pk_bf16_f32 v2, v2, v3
	v_pk_mul_f32 v[4:5], v[54:55], v[26:27] op_sel_hi:[0,1]
	v_lshlrev_b32_e32 v6, 16, v45
	v_and_b32_e32 v7, 0xffff0000, v45
	v_cvt_pk_bf16_f32 v3, v8, v9
	v_pk_mul_f32 v[8:9], v[54:55], v[28:29] op_sel_hi:[0,1]
	v_pk_mul_f32 v[4:5], v[4:5], v[66:67]
	v_pk_mul_f32 v[6:7], v[8:9], v[6:7]
	v_cvt_pk_bf16_f32 v4, v4, v5
	v_cvt_pk_bf16_f32 v5, v6, v7
	global_store_dwordx4 v[52:53], v[2:5], off offset:32
	v_pk_mul_f32 v[6:7], v[54:55], v[16:17] op_sel_hi:[0,1]
	v_pk_mul_f32 v[8:9], v[54:55], v[32:33] op_sel_hi:[0,1]
	v_lshlrev_b32_e32 v2, 16, v46
	v_and_b32_e32 v3, 0xffff0000, v46
	v_pk_mul_f32 v[4:5], v[54:55], v[14:15] op_sel_hi:[0,1]
	v_pk_mul_f32 v[2:3], v[4:5], v[2:3]
	v_lshlrev_b32_e32 v4, 16, v47
	v_and_b32_e32 v5, 0xffff0000, v47
	v_pk_mul_f32 v[4:5], v[6:7], v[4:5]
	v_cvt_pk_bf16_f32 v2, v2, v3
	v_cvt_pk_bf16_f32 v3, v4, v5
	v_lshlrev_b32_e32 v4, 16, v48
	v_and_b32_e32 v5, 0xffff0000, v48
	v_pk_mul_f32 v[6:7], v[54:55], v[30:31] op_sel_hi:[0,1]
	v_pk_mul_f32 v[4:5], v[6:7], v[4:5]
	v_lshlrev_b32_e32 v6, 16, v49
	v_and_b32_e32 v7, 0xffff0000, v49
	v_pk_mul_f32 v[6:7], v[8:9], v[6:7]
	v_cvt_pk_bf16_f32 v4, v4, v5
	v_cvt_pk_bf16_f32 v5, v6, v7
	global_store_dwordx4 v[52:53], v[2:5], off offset:48
	s_andn2_b64 exec, exec, s[84:85]
	s_cbranch_execz .LBB0_551

.LBB0_464:
	s_or_b64 exec, exec, s[6:7]
	v_ashrrev_i32_e32 v147, 31, v146
	v_lshlrev_b64 v[150:151], 10, v[146:147]
	v_lshl_add_u64 v[2:3], s[24:25], 0, v[150:151]
	v_lshlrev_b32_e32 v4, 7, v184
	v_mov_b32_e32 v5, v133
	v_lshl_add_u64 v[2:3], v[2:3], 0, v[4:5]
	v_lshl_add_u64 v[2:3], v[2:3], 0, v[134:135]
	global_load_dwordx4 v[98:101], v[2:3], off
	global_load_dwordx4 v[102:105], v[2:3], off offset:32
	global_load_dwordx4 v[106:109], v[2:3], off offset:64
	global_load_dwordx4 v[110:113], v[2:3], off offset:96
	v_readlane_b32 s98, v245, 48
	v_readlane_b32 s99, v245, 49
	v_add3_u32 v247, v150, v4, v144
	s_and_saveexec_b64 s[4:5], vcc
	s_xor_b64 s[4:5], exec, s[4:5]
	v_ashrrev_i32_e32 v4, 6, v148
	v_ashrrev_i32_e32 v149, 31, v148
	v_ashrrev_i32_e32 v5, 31, v4
	v_mad_u64_u32 v[2:3], s[6:7], v184, s26, v[148:149]
	v_mad_u64_u32 v[4:5], s[6:7], v184, s33, v[4:5]
	v_lshlrev_b64 v[2:3], 7, v[2:3]
	v_lshlrev_b64 v[4:5], 13, v[4:5]
	v_lshl_add_u64 v[2:3], s[88:89], 0, v[2:3]
	v_lshl_add_u64 v[4:5], s[90:91], 0, v[4:5]
	s_or_saveexec_b64 s[4:5], s[4:5]
	v_lshl_or_b32 v34, v6, 3, v184
	v_ashrrev_i32_e32 v35, 31, v34
	s_xor_b64 exec, exec, s[4:5]
	v_lshlrev_b64 v[4:5], 16, v[34:35]
	v_lshl_add_u64 v[2:3], s[80:81], 0, v[4:5]
	v_lshl_add_u64 v[4:5], s[92:93], 0, v[4:5]
	s_or_b64 exec, exec, s[4:5]
	v_lshl_add_u64 v[6:7], v[2:3], 0, v[132:133]
	v_lshl_add_u64 v[2:3], v[2:3], 0, v[142:143]
	v_lshl_add_u64 v[6:7], v[6:7], 0, v[138:139]
	v_lshl_add_u64 v[2:3], v[2:3], 0, v[138:139]
	global_load_dwordx4 v[6:9], v[6:7], off
	s_nop 0
	global_load_dwordx4 v[10:13], v[2:3], off
	v_lshl_add_u64 v[2:3], v[4:5], 0, v[132:133]
	v_lshl_add_u64 v[4:5], v[4:5], 0, v[142:143]
	v_lshl_add_u64 v[2:3], v[2:3], 0, v[138:139]
	v_lshl_add_u64 v[14:15], v[4:5], 0, v[138:139]
	global_load_dwordx4 v[2:5], v[2:3], off
	s_nop 0
	global_load_dwordx4 v[14:17], v[14:15], off
	s_and_saveexec_b64 s[4:5], vcc
	s_xor_b64 s[4:5], exec, s[4:5]
	s_cbranch_execz .LBB0_470
	v_add_u32_e32 v60, 64, v148
	v_ashrrev_i32_e32 v61, 31, v60
	v_mad_u64_u32 v[62:63], s[6:7], v184, s26, v[60:61]
	v_ashrrev_i32_e32 v60, 6, v60
	v_ashrrev_i32_e32 v61, 31, v60
	v_mad_u64_u32 v[60:61], s[6:7], v184, s33, v[60:61]
	v_lshlrev_b64 v[62:63], 7, v[62:63]
	v_lshlrev_b64 v[60:61], 13, v[60:61]
	v_lshl_add_u64 v[36:37], s[88:89], 0, v[62:63]
	v_lshl_add_u64 v[38:39], s[90:91], 0, v[60:61]
.LBB0_470:
	s_andn2_saveexec_b64 s[4:5], s[4:5]
	v_lshlrev_b64 v[60:61], 16, v[34:35]
	v_lshl_add_u64 v[62:63], s[80:81], 0, v[60:61]
	s_mov_b64 s[6:7], 0x2000
	v_lshl_add_u64 v[60:61], s[92:93], 0, v[60:61]
	v_lshl_add_u64 v[36:37], v[62:63], 0, s[6:7]
	v_lshl_add_u64 v[38:39], v[60:61], 0, s[6:7]
	s_or_b64 exec, exec, s[4:5]
	v_lshl_add_u64 v[60:61], v[38:39], 0, v[142:143]
	v_lshl_add_u64 v[60:61], v[60:61], 0, v[138:139]
	v_lshl_add_u64 v[62:63], v[38:39], 0, v[132:133]
	v_lshl_add_u64 v[62:63], v[62:63], 0, v[138:139]
	global_load_dwordx4 v[114:117], v[60:61], off
	global_load_dwordx4 v[118:121], v[62:63], off
	v_lshl_add_u64 v[60:61], v[36:37], 0, v[142:143]
	v_lshl_add_u64 v[60:61], v[60:61], 0, v[138:139]
	v_lshl_add_u64 v[62:63], v[36:37], 0, v[132:133]
	v_lshl_add_u64 v[62:63], v[62:63], 0, v[138:139]
	global_load_dwordx4 v[122:125], v[60:61], off
	global_load_dwordx4 v[126:129], v[62:63], off
	global_load_dwordx4 v[226:229], v247, s[98:99]
	global_load_dwordx4 v[230:233], v247, s[98:99] offset:16
	global_load_dwordx4 v[234:237], v247, s[98:99] offset:32
	global_load_dwordx4 v[238:241], v247, s[98:99] offset:48
	s_waitcnt vmcnt(11)
	ds_write_b128 v176, v[6:9]
	s_waitcnt vmcnt(10)
	ds_write_b128 v177, v[10:13]
	s_waitcnt vmcnt(9)
	ds_write2_b64 v179, v[2:3], v[4:5] offset0:128 offset1:130
	s_waitcnt vmcnt(8)
	ds_write2_b64 v180, v[14:15], v[16:17] offset0:128 offset1:130
	v_mov_b32_e32 v16, v133
	v_mov_b32_e32 v17, v133
	v_mov_b32_e32 v2, v133
	v_mov_b32_e32 v3, v133
	v_mov_b32_e32 v4, v133
	v_mov_b32_e32 v5, v133
	v_mov_b32_e32 v6, v133
	v_mov_b32_e32 v7, v133
	v_mov_b32_e32 v8, v133
	v_mov_b32_e32 v9, v133
	v_mov_b32_e32 v10, v133
	v_mov_b32_e32 v11, v133
	v_mov_b32_e32 v12, v133
	v_mov_b32_e32 v13, v133
	v_mov_b32_e32 v14, v133
	v_mov_b32_e32 v15, v133
	v_mov_b64_e32 v[32:33], v[16:17]
	v_cmp_lt_i32_e32 vcc, 0, v183
	v_mov_b32_e32 v149, 0
	v_mov_b64_e32 v[30:31], v[14:15]
	v_mov_b64_e32 v[28:29], v[12:13]
	v_mov_b64_e32 v[26:27], v[10:11]
	v_mov_b64_e32 v[24:25], v[8:9]
	v_mov_b64_e32 v[22:23], v[6:7]
	v_mov_b64_e32 v[20:21], v[4:5]
	v_mov_b64_e32 v[18:19], v[2:3]
	s_and_saveexec_b64 s[82:83], vcc
	s_cbranch_execz .LBB0_456
	v_lshlrev_b64 v[2:3], 16, v[34:35]
	v_lshl_add_u64 v[156:157], s[80:81], 0, v[2:3]
	v_lshl_add_u64 v[158:159], s[92:93], 0, v[2:3]
	v_sub_u32_e32 v2, v171, v42
	v_lshl_add_u32 v187, v2, 2, v160
	v_sub_u32_e32 v2, v171, v41
	v_and_b32_e32 v3, -16, v2
	s_movk_i32 s3, 0xffe0
	v_cmp_eq_u32_e64 s[6:7], s3, v3
	s_movk_i32 s3, 0xffef
	v_add_u32_e32 v4, 1, v2
	v_cmp_lt_u32_e64 s[38:39], s3, v2
	s_movk_i32 s3, 0xffd0
	v_cmp_gt_u32_e64 s[8:9], 16, v4
	v_add_u32_e32 v4, 33, v2
	v_cmp_eq_u32_e64 s[40:41], s3, v3
	v_add_u32_e32 v3, 17, v2
	v_cmp_gt_u32_e64 s[10:11], 16, v4
	v_add_u32_e32 v4, 2, v2
	v_cmp_gt_u32_e64 s[42:43], 16, v3
	v_add_u32_e32 v3, 49, v2
	v_cmp_gt_u32_e64 s[12:13], 16, v4
	v_add_u32_e32 v4, 34, v2
	v_cmp_gt_u32_e64 s[44:45], 16, v3
	v_add_u32_e32 v3, 18, v2
	v_cmp_gt_u32_e64 s[14:15], 16, v4
	v_add_u32_e32 v4, 3, v2
	v_cmp_gt_u32_e64 s[46:47], 16, v3
	v_add_u32_e32 v3, 50, v2
	v_cmp_gt_u32_e64 s[16:17], 16, v4
	v_add_u32_e32 v4, 35, v2
	v_cmp_gt_u32_e64 s[48:49], 16, v3
	v_add_u32_e32 v3, 19, v2
	v_cmp_gt_u32_e64 s[18:19], 16, v4
	v_add_u32_e32 v4, 8, v2
	v_cmp_gt_u32_e64 s[50:51], 16, v3
	v_add_u32_e32 v3, 51, v2
	v_cmp_gt_u32_e64 s[20:21], 16, v4
	v_add_u32_e32 v4, 40, v2
	v_cmp_gt_u32_e64 s[52:53], 16, v3
	v_add_u32_e32 v3, 24, v2
	v_cmp_gt_u32_e64 s[22:23], 16, v4
	v_add_u32_e32 v4, 9, v2
	v_cmp_gt_u32_e64 s[54:55], 16, v3
	v_add_u32_e32 v3, 56, v2
	v_cmp_gt_u32_e64 s[24:25], 16, v4
	v_add_u32_e32 v4, 41, v2
	v_cmp_gt_u32_e64 s[56:57], 16, v3
	v_add_u32_e32 v3, 25, v2
	v_cmp_gt_u32_e64 s[26:27], 16, v4
	v_add_u32_e32 v4, 10, v2
	v_cmp_gt_u32_e64 s[58:59], 16, v3
	v_add_u32_e32 v3, 57, v2
	v_cmp_gt_u32_e64 s[28:29], 16, v4
	v_add_u32_e32 v4, 42, v2
	v_cmp_gt_u32_e64 s[60:61], 16, v3
	v_add_u32_e32 v3, 26, v2
	v_cmp_gt_u32_e64 s[30:31], 16, v4
	v_add_u32_e32 v4, 11, v2
	v_cmp_gt_u32_e64 s[62:63], 16, v3
	v_add_u32_e32 v3, 58, v2
	v_cmp_gt_u32_e64 s[4:5], 16, v2
	v_cmp_gt_u32_e64 s[34:35], 16, v4
	v_add_u32_e32 v4, 43, v2
	v_cmp_gt_u32_e64 s[64:65], 16, v3
	v_add_u32_e32 v3, 27, v2
	v_add_u32_e32 v2, 59, v2
	v_cmp_gt_u32_e64 s[66:67], 16, v3
	v_cmp_gt_u32_e64 s[68:69], 16, v2
	v_mul_u32_u24_e32 v2, 31, v145
	v_mul_u32_u24_e32 v3, 31, v40
	v_sub_u32_e32 v2, v2, v3
	v_mov_b32_e32 v16, v133
	v_mov_b32_e32 v17, v133
	v_cmp_gt_u32_e64 s[36:37], 16, v4
	v_subrev_u32_e32 v188, 31, v2
	v_mov_b32_e32 v2, v133
	v_mov_b32_e32 v3, v133
	v_mov_b32_e32 v4, v133
	v_mov_b32_e32 v5, v133
	v_mov_b32_e32 v6, v133
	v_mov_b32_e32 v7, v133
	v_mov_b32_e32 v8, v133
	v_mov_b32_e32 v9, v133
	v_mov_b32_e32 v10, v133
	v_mov_b32_e32 v11, v133
	v_mov_b32_e32 v12, v133
	v_mov_b32_e32 v13, v133
	v_mov_b32_e32 v14, v133
	v_mov_b32_e32 v15, v133
	v_mov_b64_e32 v[32:33], v[16:17]
	v_add_u32_e32 v185, -1, v183
	v_mul_hi_u32_u24_e32 v153, 0x6000, v184
	v_mul_u32_u24_e32 v152, 0x6000, v184
	v_mul_hi_u32_u24_e32 v155, 0x180, v184
	v_mul_u32_u24_e32 v154, 0x180, v184
	v_add_u32_e32 v186, 8, v182
	v_add_u32_e32 v189, -8, v145
	s_mov_b32 s3, 0
	v_mov_b32_e32 v190, 0xff800000
	v_mov_b32_e32 v149, 0
	s_mov_b64 s[70:71], 0
	s_xor_b64 s[86:87], s[0:1], -1
	v_mov_b64_e32 v[30:31], v[14:15]
	v_mov_b64_e32 v[28:29], v[12:13]
	v_mov_b64_e32 v[26:27], v[10:11]
	v_mov_b64_e32 v[24:25], v[8:9]
	v_mov_b64_e32 v[22:23], v[6:7]
	v_mov_b64_e32 v[20:21], v[4:5]
	v_mov_b64_e32 v[18:19], v[2:3]
	v_mov_b32_e32 v36, 0
	v_mov_b32_e32 v38, 0
	s_mov_b64 s[72:73], s[86:87]
	s_and_saveexec_b64 s[76:77], s[72:73]
	s_xor_b64 s[72:73], exec, s[76:77]
	s_cbranch_execz .Laddr478_a
	v_add_u32_e32 v34, v36, v145
	v_lshl_add_u32 v34, v34, 6, v181
	v_cndmask_b32_e64 v34, v38, v34, s[0:1]
	v_add_u32_e32 v36, v34, v148
	v_ashrrev_i32_e32 v37, 31, v36
	v_lshl_add_u64 v[34:35], v[152:153], 0, v[36:37]
	v_ashrrev_i32_e32 v36, 6, v36
	v_lshlrev_b64 v[34:35], 7, v[34:35]
	v_ashrrev_i32_e32 v37, 31, v36
	v_lshl_add_u64 v[34:35], s[88:89], 0, v[34:35]
	v_lshl_add_u64 v[36:37], v[154:155], 0, v[36:37]
